# grid barrier: L1 invalidate (buffer_inv sc1) moved off the release path - issued by wave 1 at arrival, overlapping the arrival atomics; tid0 no longer invalidates after release
# speedup vs baseline: 1.0262x; 1.0161x over previous
.LBB0_199:
	s_or_b64 exec, exec, s[4:5]
	s_waitcnt vmcnt(0)
	v_mov_b32_e32 v1, v147
	s_waitcnt vmcnt(63) expcnt(7) lgkmcnt(15)
	s_barrier
	s_nop 0
	v_readfirstlane_b32 vcc_lo, v1
	s_nop 1
	s_cmp_eq_u32 vcc_lo, 64
	s_cbranch_scc0 .Lxb_noinv_0
	buffer_inv sc1
	s_waitcnt vmcnt(0)
.Lxb_noinv_0:
	v_cmp_eq_u32_e32 vcc, 0, v1
	s_and_saveexec_b64 s[4:5], vcc
	s_cbranch_execz .LBB0_251
	s_add_i32 s8, 0, 0x23f00
	v_mov_b32_e32 v1, s8
	s_load_dwordx2 s[6:7], s[0:1], 0x98
	s_waitcnt vmcnt(0) expcnt(0) lgkmcnt(0)
	s_getreg_b32 s3, hwreg(HW_REG_XCC_ID, 0, 4)
	ds_read_b32 v3, v1
	s_add_i32 s8, 0, 0x23f04
	v_mov_b32_e32 v1, s8
	ds_read_b32 v1, v1
	s_and_b32 s3, s3, 15
	s_waitcnt lgkmcnt(1)
	v_cmp_ne_u32_e32 vcc, 0, v3
	s_cbranch_vccnz .LBB0_215
	s_add_u32 s8, s6, 0x4200
	s_addc_u32 s9, s7, 0
	s_add_u32 s12, s6, 0x4400
	s_addc_u32 s13, s7, 0
	s_add_u32 s14, s6, 0x4500
	s_addc_u32 s15, s7, 0
	s_add_u32 s16, s6, 0x4600
	s_addc_u32 s17, s7, 0
	s_add_u32 s18, s6, 0x4700
	s_addc_u32 s19, s7, 0
	s_add_u32 s20, s6, 0x4800
	s_addc_u32 s21, s7, 0
	s_add_u32 s22, s6, 0x4900
	s_addc_u32 s23, s7, 0
	s_add_u32 s24, s6, 0x4a00
	s_addc_u32 s25, s7, 0
	s_add_u32 s26, s6, 0x4b00
	s_addc_u32 s27, s7, 0
	s_add_u32 s34, s6, 0x4c00
	s_addc_u32 s35, s7, 0
	s_add_u32 s36, s6, 0x4d00
	s_addc_u32 s37, s7, 0
	s_add_u32 s38, s6, 0x4e00
	s_addc_u32 s39, s7, 0
	s_add_u32 s40, s6, 0x4f00
	s_addc_u32 s41, s7, 0
	s_add_u32 s42, s6, 0x5000
	s_addc_u32 s43, s7, 0
	s_add_u32 s44, s6, 0x5100
	s_addc_u32 s45, s7, 0
	s_add_u32 s46, s6, 0x5200
	s_addc_u32 s47, s7, 0
	s_mul_i32 s30, s29, s2
	s_add_u32 s48, s6, 0x5300
	s_mul_i32 s30, s30, s28
	s_addc_u32 s49, s7, 0
	s_mov_b32 s31, 1
	v_mov_b32_e32 v17, 0
	s_branch .LBB0_203

.LBB0_230:
	s_or_b64 exec, exec, s[14:15]
	s_waitcnt vmcnt(0)
	s_waitcnt vmcnt(0)

.LBB0_248:
	s_or_b64 exec, exec, s[6:7]
	s_mov_b64 s[6:7], exec
	v_mbcnt_lo_u32_b32 v1, s6, 0
	v_mbcnt_hi_u32_b32 v1, s7, v1
	v_cmp_eq_u32_e32 vcc, 0, v1
	s_waitcnt vmcnt(0)
	s_and_saveexec_b64 s[12:13], vcc
	s_cbranch_execz .LBB0_250
	s_bcnt1_i32_b64 s3, s[6:7]
	v_mov_b32_e32 v1, 0x2000
	v_mov_b32_e32 v2, s3
	global_atomic_add v1, v2, s[8:9] offset:1024

.LBB0_280:
	s_or_b64 exec, exec, s[16:17]
	s_mov_b64 s[8:9], s[0:1]
	s_waitcnt vmcnt(0)
	v_mov_b32_e32 v0, v147
	s_barrier
	s_nop 0
	v_readfirstlane_b32 vcc_lo, v0
	s_nop 1
	s_cmp_eq_u32 vcc_lo, 64
	s_cbranch_scc0 .Lxb_noinv_1
	buffer_inv sc1
	s_waitcnt vmcnt(0)
.Lxb_noinv_1:
	v_cmp_eq_u32_e32 vcc, 0, v0
	s_and_saveexec_b64 s[0:1], vcc
	s_cbranch_execz .LBB0_332
	v_readlane_b32 s6, v255, 3
	s_load_dwordx2 s[4:5], s[8:9], 0x98
	s_waitcnt vmcnt(0) expcnt(0) lgkmcnt(0)
	v_mov_b32_e32 v0, s6
	s_getreg_b32 s2, hwreg(HW_REG_XCC_ID, 0, 4)
	ds_read_b32 v2, v0
	v_readlane_b32 s6, v255, 4
	s_and_b32 s2, s2, 15
	s_waitcnt lgkmcnt(0)
	v_cmp_ne_u32_e32 vcc, 0, v2
	v_mov_b32_e32 v0, s6
	ds_read_b32 v0, v0
	s_cbranch_vccnz .LBB0_296
	s_add_u32 s6, s4, 0x4200
	s_addc_u32 s7, s5, 0
	s_add_u32 s10, s4, 0x4400
	s_addc_u32 s11, s5, 0
	s_add_u32 s12, s4, 0x4500
	s_addc_u32 s13, s5, 0
	s_add_u32 s14, s4, 0x4600
	s_addc_u32 s15, s5, 0
	s_add_u32 s16, s4, 0x4700
	s_addc_u32 s17, s5, 0
	s_add_u32 s18, s4, 0x4800
	s_addc_u32 s19, s5, 0
	s_add_u32 s20, s4, 0x4900
	s_addc_u32 s21, s5, 0
	s_add_u32 s22, s4, 0x4a00
	s_addc_u32 s23, s5, 0
	s_add_u32 s24, s4, 0x4b00
	s_addc_u32 s25, s5, 0
	s_add_u32 s42, s4, 0x4c00
	s_addc_u32 s43, s5, 0
	s_add_u32 s54, s4, 0x4d00
	s_addc_u32 s55, s5, 0
	s_add_u32 s56, s4, 0x4e00
	s_addc_u32 s57, s5, 0
	s_add_u32 s58, s4, 0x4f00
	s_addc_u32 s59, s5, 0
	s_add_u32 s60, s4, 0x5000
	s_addc_u32 s61, s5, 0
	s_add_u32 s62, s4, 0x5100
	s_addc_u32 s63, s5, 0
	s_add_u32 s64, s4, 0x5200
	s_addc_u32 s65, s5, 0
	s_add_u32 s74, s4, 0x5300
	s_addc_u32 s75, s5, 0
	s_mov_b32 s26, 1
	s_branch .LBB0_284

.LBB0_311:
	s_or_b64 exec, exec, s[12:13]
	s_waitcnt vmcnt(0)
	s_waitcnt vmcnt(0)

.LBB0_329:
	s_or_b64 exec, exec, s[4:5]
	s_mov_b64 s[4:5], exec
	v_mbcnt_lo_u32_b32 v0, s4, 0
	v_mbcnt_hi_u32_b32 v0, s5, v0
	v_cmp_eq_u32_e32 vcc, 0, v0
	s_waitcnt vmcnt(0)
	s_and_saveexec_b64 s[10:11], vcc
	s_cbranch_execz .LBB0_331
	s_bcnt1_i32_b64 s2, s[4:5]
	v_mov_b32_e32 v0, s2
	global_atomic_add v186, v0, s[6:7] offset:1024

.LBB0_385:
	s_waitcnt vmcnt(0)
	v_mov_b32_e32 v0, v147
	s_waitcnt vmcnt(0)
	s_barrier
	s_nop 0
	v_readfirstlane_b32 vcc_lo, v0
	s_nop 1
	s_cmp_eq_u32 vcc_lo, 64
	s_cbranch_scc0 .Lxb_noinv_2
	buffer_inv sc1
	s_waitcnt vmcnt(0)
.Lxb_noinv_2:
	v_cmp_eq_u32_e32 vcc, 0, v0
	s_and_saveexec_b64 s[0:1], vcc
	s_xor_b64 s[0:1], exec, s[0:1]
	s_cbranch_execz .LBB0_438
	v_readlane_b32 s7, v255, 3
	s_load_dwordx2 s[4:5], s[8:9], 0x98
	s_waitcnt vmcnt(0) expcnt(0) lgkmcnt(0)
	v_mov_b32_e32 v0, s7
	s_getreg_b32 s6, hwreg(HW_REG_XCC_ID, 0, 4)
	ds_read_b32 v2, v0
	v_readlane_b32 s7, v255, 4
	s_and_b32 s26, s6, 15
	s_waitcnt lgkmcnt(0)
	v_cmp_ne_u32_e32 vcc, 0, v2
	v_mov_b32_e32 v0, s7
	ds_read_b32 v0, v0
	s_cbranch_vccnz .LBB0_401
	s_add_u32 s6, s4, 0x4200
	s_addc_u32 s7, s5, 0
	s_add_u32 s10, s4, 0x4400
	s_addc_u32 s11, s5, 0
	s_add_u32 s12, s4, 0x4500
	s_addc_u32 s13, s5, 0
	s_add_u32 s14, s4, 0x4600
	s_addc_u32 s15, s5, 0
	s_add_u32 s16, s4, 0x4700
	s_addc_u32 s17, s5, 0
	s_add_u32 s18, s4, 0x4800
	s_addc_u32 s19, s5, 0
	s_add_u32 s20, s4, 0x4900
	s_addc_u32 s21, s5, 0
	s_add_u32 s22, s4, 0x4a00
	s_addc_u32 s23, s5, 0
	s_add_u32 s24, s4, 0x4b00
	s_addc_u32 s25, s5, 0
	s_add_u32 s42, s4, 0x4c00
	s_addc_u32 s43, s5, 0
	s_add_u32 s54, s4, 0x4d00
	s_addc_u32 s55, s5, 0
	s_add_u32 s56, s4, 0x4e00
	s_addc_u32 s57, s5, 0
	s_add_u32 s58, s4, 0x4f00
	s_addc_u32 s59, s5, 0
	s_add_u32 s60, s4, 0x5000
	s_addc_u32 s61, s5, 0
	s_add_u32 s62, s4, 0x5100
	s_addc_u32 s63, s5, 0
	s_add_u32 s64, s4, 0x5200
	s_addc_u32 s65, s5, 0
	s_add_u32 s88, s4, 0x5300
	s_addc_u32 s89, s5, 0
	s_mov_b32 s27, 1
	s_branch .LBB0_389

.LBB0_434:
	s_or_b64 exec, exec, s[4:5]
	s_mov_b64 s[4:5], exec
	v_mbcnt_lo_u32_b32 v0, s4, 0
	v_mbcnt_hi_u32_b32 v0, s5, v0
	v_cmp_eq_u32_e32 vcc, 0, v0
	s_waitcnt vmcnt(0)
	s_and_saveexec_b64 s[12:13], vcc
	s_cbranch_execz .LBB0_436
	s_bcnt1_i32_b64 s4, s[4:5]
	v_mov_b32_e32 v0, s4
	global_atomic_add v186, v0, s[6:7] offset:1024

.Lxb_noinv_3:
	v_cmp_eq_u32_e32 vcc, 0, v0
	s_and_saveexec_b64 s[4:5], vcc
	s_xor_b64 s[4:5], exec, s[4:5]
	s_cbranch_execz .LBB0_519
	v_readlane_b32 s8, v255, 3
	s_load_dwordx2 s[6:7], s[0:1], 0x98
	s_waitcnt vmcnt(0) expcnt(0) lgkmcnt(0)
	v_mov_b32_e32 v0, s8
	s_getreg_b32 s2, hwreg(HW_REG_XCC_ID, 0, 4)
	ds_read_b32 v2, v0
	v_readlane_b32 s8, v255, 4
	s_and_b32 s2, s2, 15
	s_waitcnt lgkmcnt(0)
	v_cmp_ne_u32_e32 vcc, 0, v2
	v_mov_b32_e32 v0, s8
	ds_read_b32 v0, v0
	s_cbranch_vccnz .LBB0_482
	s_add_u32 s8, s6, 0x4200
	s_addc_u32 s9, s7, 0
	s_add_u32 s12, s6, 0x4400
	s_addc_u32 s13, s7, 0
	s_add_u32 s14, s6, 0x4500
	s_addc_u32 s15, s7, 0
	s_add_u32 s16, s6, 0x4600
	s_addc_u32 s17, s7, 0
	s_add_u32 s18, s6, 0x4700
	s_addc_u32 s19, s7, 0
	s_add_u32 s20, s6, 0x4800
	s_addc_u32 s21, s7, 0
	s_add_u32 s22, s6, 0x4900
	s_addc_u32 s23, s7, 0
	s_add_u32 s24, s6, 0x4a00
	s_addc_u32 s25, s7, 0
	s_add_u32 s42, s6, 0x4b00
	s_addc_u32 s43, s7, 0
	s_add_u32 s54, s6, 0x4c00
	s_addc_u32 s55, s7, 0
	s_add_u32 s56, s6, 0x4d00
	s_addc_u32 s57, s7, 0
	s_add_u32 s58, s6, 0x4e00
	s_addc_u32 s59, s7, 0
	s_add_u32 s60, s6, 0x4f00
	s_addc_u32 s61, s7, 0
	s_add_u32 s62, s6, 0x5000
	s_addc_u32 s63, s7, 0
	s_add_u32 s64, s6, 0x5100
	s_addc_u32 s65, s7, 0
	s_add_u32 s86, s6, 0x5200
	s_addc_u32 s87, s7, 0
	s_add_u32 s88, s6, 0x5300
	s_addc_u32 s89, s7, 0
	s_mov_b32 s26, 1
	s_branch .LBB0_470

.LBB0_515:
	s_or_b64 exec, exec, s[6:7]
	s_mov_b64 s[6:7], exec
	v_mbcnt_lo_u32_b32 v0, s6, 0
	v_mbcnt_hi_u32_b32 v0, s7, v0
	v_cmp_eq_u32_e32 vcc, 0, v0
	s_waitcnt vmcnt(0)
	s_and_saveexec_b64 s[14:15], vcc
	s_cbranch_execz .LBB0_517
	s_bcnt1_i32_b64 s2, s[6:7]
	v_mov_b32_e32 v0, s2
	global_atomic_add v186, v0, s[8:9] offset:1024

.LBB0_523:
	s_or_b64 exec, exec, s[8:9]
	s_waitcnt vmcnt(0)
	v_mov_b32_e32 v0, v147
	s_barrier
	s_nop 0
	v_readfirstlane_b32 vcc_lo, v0
	s_nop 1
	s_cmp_eq_u32 vcc_lo, 64
	s_cbranch_scc0 .Lxb_noinv_4
	buffer_inv sc1
	s_waitcnt vmcnt(0)
.Lxb_noinv_4:
	v_cmp_eq_u32_e32 vcc, 0, v0
	s_and_saveexec_b64 s[4:5], vcc
	s_cbranch_execz .LBB0_575
	v_readlane_b32 s8, v255, 3
	s_load_dwordx2 s[6:7], s[16:17], 0x98
	s_waitcnt vmcnt(0) expcnt(0) lgkmcnt(0)
	v_mov_b32_e32 v0, s8
	s_getreg_b32 s2, hwreg(HW_REG_XCC_ID, 0, 4)
	ds_read_b32 v2, v0
	v_readlane_b32 s8, v255, 4
	s_and_b32 s2, s2, 15
	s_waitcnt lgkmcnt(0)
	v_cmp_ne_u32_e32 vcc, 0, v2
	v_mov_b32_e32 v0, s8
	ds_read_b32 v0, v0
	s_cbranch_vccnz .LBB0_539
	s_add_u32 s8, s6, 0x4200
	s_addc_u32 s9, s7, 0
	s_add_u32 s10, s6, 0x4400
	s_addc_u32 s11, s7, 0
	s_add_u32 s12, s6, 0x4500
	s_addc_u32 s13, s7, 0
	s_add_u32 s14, s6, 0x4600
	s_addc_u32 s15, s7, 0
	s_add_u32 s18, s6, 0x4700
	s_addc_u32 s19, s7, 0
	s_add_u32 s20, s6, 0x4800
	s_addc_u32 s21, s7, 0
	s_add_u32 s22, s6, 0x4900
	s_addc_u32 s23, s7, 0
	s_add_u32 s24, s6, 0x4a00
	s_addc_u32 s25, s7, 0
	s_add_u32 s42, s6, 0x4b00
	s_addc_u32 s43, s7, 0
	s_add_u32 s54, s6, 0x4c00
	s_addc_u32 s55, s7, 0
	s_add_u32 s56, s6, 0x4d00
	s_addc_u32 s57, s7, 0
	s_add_u32 s58, s6, 0x4e00
	s_addc_u32 s59, s7, 0
	s_add_u32 s60, s6, 0x4f00
	s_addc_u32 s61, s7, 0
	s_add_u32 s62, s6, 0x5000
	s_addc_u32 s63, s7, 0
	s_add_u32 s64, s6, 0x5100
	s_addc_u32 s65, s7, 0
	s_add_u32 s88, s6, 0x5200
	s_addc_u32 s89, s7, 0
	s_add_u32 s90, s6, 0x5300
	s_addc_u32 s91, s7, 0
	s_mov_b32 s26, 1
	s_branch .LBB0_527

.LBB0_572:
	s_or_b64 exec, exec, s[6:7]
	s_mov_b64 s[6:7], exec
	v_mbcnt_lo_u32_b32 v0, s6, 0
	v_mbcnt_hi_u32_b32 v0, s7, v0
	v_cmp_eq_u32_e32 vcc, 0, v0
	s_waitcnt vmcnt(0)
	s_and_saveexec_b64 s[10:11], vcc
	s_cbranch_execz .LBB0_574
	s_bcnt1_i32_b64 s2, s[6:7]
	v_mov_b32_e32 v0, s2
	global_atomic_add v186, v0, s[8:9] offset:1024

.LBB0_921:
	s_waitcnt vmcnt(0)
	v_mov_b32_e32 v0, v147
	s_waitcnt vmcnt(0) lgkmcnt(0)
	s_barrier
	s_nop 0
	v_readfirstlane_b32 vcc_lo, v0
	s_nop 1
	s_cmp_eq_u32 vcc_lo, 64
	s_cbranch_scc0 .Lxb_noinv_5
	buffer_inv sc1
	s_waitcnt vmcnt(0)

.LBB0_1093:
	s_waitcnt vmcnt(0)
	v_mov_b32_e32 v0, v147
	s_barrier
	s_nop 0
	v_readfirstlane_b32 vcc_lo, v0
	s_nop 1
	s_cmp_eq_u32 vcc_lo, 64
	s_cbranch_scc0 .Lxb_noinv_6
	buffer_inv sc1
	s_waitcnt vmcnt(0)
.Lxb_noinv_6:
	v_cmp_eq_u32_e32 vcc, 0, v0
	s_and_saveexec_b64 s[4:5], vcc
	s_cbranch_execz .LBB0_1145
	v_readlane_b32 s10, v255, 3
	s_load_dwordx2 s[6:7], s[8:9], 0x98
	s_waitcnt vmcnt(0) expcnt(0) lgkmcnt(0)
	v_mov_b32_e32 v0, s10
	s_getreg_b32 s2, hwreg(HW_REG_XCC_ID, 0, 4)
	ds_read_b32 v2, v0
	v_readlane_b32 s10, v255, 4
	s_and_b32 s2, s2, 15
	s_waitcnt lgkmcnt(0)
	v_cmp_ne_u32_e32 vcc, 0, v2
	v_mov_b32_e32 v0, s10
	ds_read_b32 v0, v0
	s_cbranch_vccnz .LBB0_1109
	s_add_u32 s10, s6, 0x4200
	s_addc_u32 s11, s7, 0
	s_add_u32 s12, s6, 0x4400
	s_addc_u32 s13, s7, 0
	s_add_u32 s14, s6, 0x4500
	s_addc_u32 s15, s7, 0
	s_add_u32 s16, s6, 0x4600
	s_addc_u32 s17, s7, 0
	s_add_u32 s18, s6, 0x4700
	s_addc_u32 s19, s7, 0
	s_add_u32 s20, s6, 0x4800
	s_addc_u32 s21, s7, 0
	s_add_u32 s22, s6, 0x4900
	s_addc_u32 s23, s7, 0
	s_add_u32 s24, s6, 0x4a00
	s_addc_u32 s25, s7, 0
	s_add_u32 s42, s6, 0x4b00
	s_addc_u32 s43, s7, 0
	s_add_u32 s54, s6, 0x4c00
	s_addc_u32 s55, s7, 0
	s_add_u32 s56, s6, 0x4d00
	s_addc_u32 s57, s7, 0
	s_add_u32 s58, s6, 0x4e00
	s_addc_u32 s59, s7, 0
	s_add_u32 s60, s6, 0x4f00
	s_addc_u32 s61, s7, 0
	s_add_u32 s62, s6, 0x5000
	s_addc_u32 s63, s7, 0
	s_add_u32 s64, s6, 0x5100
	s_addc_u32 s65, s7, 0
	s_add_u32 s88, s6, 0x5200
	s_addc_u32 s89, s7, 0
	s_add_u32 s90, s6, 0x5300
	s_addc_u32 s91, s7, 0
	s_mov_b32 s26, 1
	s_branch .LBB0_1097

.LBB0_1142:
	s_or_b64 exec, exec, s[6:7]
	s_mov_b64 s[6:7], exec
	v_mbcnt_lo_u32_b32 v0, s6, 0
	v_mbcnt_hi_u32_b32 v0, s7, v0
	v_cmp_eq_u32_e32 vcc, 0, v0
	s_waitcnt vmcnt(0)
	s_and_saveexec_b64 s[12:13], vcc
	s_cbranch_execz .LBB0_1144
	s_bcnt1_i32_b64 s2, s[6:7]
	v_mov_b32_e32 v0, s2
	global_atomic_add v186, v0, s[10:11] offset:1024

.Lxb_noinv_7:
	v_cmp_eq_u32_e32 vcc, 0, v0
	s_and_saveexec_b64 s[4:5], vcc
	s_xor_b64 s[4:5], exec, s[4:5]
	s_cbranch_execz .LBB0_1222
	v_readlane_b32 s10, v255, 3
	s_load_dwordx2 s[6:7], s[8:9], 0x98
	s_waitcnt vmcnt(0) expcnt(0) lgkmcnt(0)
	v_mov_b32_e32 v0, s10
	s_getreg_b32 s2, hwreg(HW_REG_XCC_ID, 0, 4)
	ds_read_b32 v2, v0
	v_readlane_b32 s10, v255, 4
	s_and_b32 s2, s2, 15
	s_waitcnt lgkmcnt(0)
	v_cmp_ne_u32_e32 vcc, 0, v2
	v_mov_b32_e32 v0, s10
	ds_read_b32 v0, v0
	s_cbranch_vccnz .LBB0_1185
	s_add_u32 s10, s6, 0x4200
	s_addc_u32 s11, s7, 0
	s_add_u32 s12, s6, 0x4400
	s_addc_u32 s13, s7, 0
	s_add_u32 s14, s6, 0x4500
	s_addc_u32 s15, s7, 0
	s_add_u32 s16, s6, 0x4600
	s_addc_u32 s17, s7, 0
	s_add_u32 s18, s6, 0x4700
	s_addc_u32 s19, s7, 0
	s_add_u32 s20, s6, 0x4800
	s_addc_u32 s21, s7, 0
	s_add_u32 s22, s6, 0x4900
	s_addc_u32 s23, s7, 0
	s_add_u32 s24, s6, 0x4a00
	s_addc_u32 s25, s7, 0
	s_add_u32 s42, s6, 0x4b00
	s_addc_u32 s43, s7, 0
	s_add_u32 s54, s6, 0x4c00
	s_addc_u32 s55, s7, 0
	s_add_u32 s56, s6, 0x4d00
	s_addc_u32 s57, s7, 0
	s_add_u32 s58, s6, 0x4e00
	s_addc_u32 s59, s7, 0
	s_add_u32 s60, s6, 0x4f00
	s_addc_u32 s61, s7, 0
	s_add_u32 s62, s6, 0x5000
	s_addc_u32 s63, s7, 0
	s_add_u32 s64, s6, 0x5100
	s_addc_u32 s65, s7, 0
	s_add_u32 s88, s6, 0x5200
	s_addc_u32 s89, s7, 0
	s_add_u32 s90, s6, 0x5300
	s_addc_u32 s91, s7, 0
	s_mov_b32 s26, 1
	s_branch .LBB0_1173

.LBB0_1218:
	s_or_b64 exec, exec, s[6:7]
	s_mov_b64 s[6:7], exec
	v_mbcnt_lo_u32_b32 v0, s6, 0
	v_mbcnt_hi_u32_b32 v0, s7, v0
	v_cmp_eq_u32_e32 vcc, 0, v0
	s_waitcnt vmcnt(0)
	s_and_saveexec_b64 s[14:15], vcc
	s_cbranch_execz .LBB0_1220
	s_bcnt1_i32_b64 s2, s[6:7]
	v_mov_b32_e32 v0, s2
	global_atomic_add v186, v0, s[10:11] offset:1024

.LBB0_1225:
	s_or_b64 exec, exec, s[10:11]
	s_waitcnt vmcnt(0)
	v_mov_b32_e32 v0, v147
	s_barrier
	s_nop 0
	v_readfirstlane_b32 vcc_lo, v0
	s_nop 1
	s_cmp_eq_u32 vcc_lo, 64
	s_cbranch_scc0 .Lxb_noinv_8
	buffer_inv sc1
	s_waitcnt vmcnt(0)

.LBB0_1274:
	s_or_b64 exec, exec, s[6:7]
	s_mov_b64 s[6:7], exec
	v_mbcnt_lo_u32_b32 v0, s6, 0
	v_mbcnt_hi_u32_b32 v0, s7, v0
	v_cmp_eq_u32_e32 vcc, 0, v0
	s_waitcnt vmcnt(0)
	s_and_saveexec_b64 s[12:13], vcc
	s_cbranch_execz .LBB0_333
	s_bcnt1_i32_b64 s2, s[6:7]
	v_mov_b32_e32 v0, s2
	global_atomic_add v186, v0, s[10:11] offset:1024
	s_branch .LBB0_333
